# first (compiler) barrier polls also sleep 127 between polls
# speedup vs baseline: 1.0290x; 1.0013x over previous
.LBB0_106:
	s_and_b32 s3, s2, 0xff
	s_mov_b64 s[20:21], -1
	s_cmp_lg_u32 s3, 0
	s_mov_b64 s[24:25], -1
	s_sleep 127
	s_cbranch_scc0 .LBB0_109
	s_and_b64 vcc, exec, s[24:25]
	s_cbranch_vccz .LBB0_105

.LBB0_123:
	s_and_b32 s3, s2, 0xff
	s_cmp_lg_u32 s3, 0
	s_mov_b64 s[22:23], -1
	s_sleep 127
	s_cbranch_scc0 .LBB0_126
	s_mov_b64 s[24:25], -1
	s_and_b64 vcc, exec, s[22:23]
	s_cbranch_vccz .LBB0_122
